# compress position-sum and cumsum item load chains de-serialized (batched loads, counted waits)
# speedup vs baseline: 1.0218x; 1.0049x over previous
; DI float bf2f(u16 v) { return (float)__builtin_bit_cast(_Float16, v); }
; DI int TID() { int t = threadIdx.x; asm volatile("" : "+v"(t)); return t; }
; DI void cumsum_item(const Params& p, int l, int item, char* lds) {
;   const int hd = item & 7, b = item >> 3;
;   float* part = (float*)lds;
;   const int tid = TID();
;   const float bfv = p.b_forget[l * 8 + hd];
;   const u16* zf = p.z + ((size_t)b * S_ + tid * 16) * ZS + FA + hd;
;   float v[16], run = 0.f;
; #pragma unroll
;   for (int i = 0; i < 16; ++i) {
;     const float f = bf2f(zf[(size_t)i * ZS]) + bfv;
;     const float ls = fminf(f, 0.f) - __logf(1.f + __expf(-fabsf(f)));
;     run += ls;
;     v[i] = run;
.LBB0_333:
	s_and_b64 vcc, exec, s[0:1]
	s_cbranch_vccz .LBB0_493
	s_and_b32 s8, s12, 7
	s_or_b32 s24, s8, s3
	v_readlane_b32 s36, v251, 2
	s_add_i32 s10, s12, 0xfffff7e0
	s_lshl_b64 s[0:1], s[24:25], 2
	v_readlane_b32 s42, v251, 8
	v_readlane_b32 s43, v251, 9
	s_add_u32 s0, s42, s0
	v_mov_b32_e32 v20, v209
	s_addc_u32 s1, s43, s1
	global_load_dword v0, v1, s[0:1]
	s_lshl_b32 s0, s10, 9
	v_lshlrev_b32_e32 v2, 4, v20
	v_readlane_b32 s80, v253, 12
	s_and_b32 s24, s0, 0x3000
	v_ashrrev_i32_e32 v3, 31, v2
	v_readlane_b32 s86, v253, 18
	v_readlane_b32 s87, v253, 19
	v_lshl_add_u64 v[4:5], v[2:3], 0, s[24:25]
	s_lshl_b32 s24, s8, 1
	v_mov_b64_e32 v[6:7], s[86:87]
	v_mad_u64_u32 v[6:7], s[0:1], v4, s75, v[6:7]
	v_mad_i32_i24 v7, v5, s75, v7
	v_lshl_add_u64 v[10:11], v[6:7], 0, s[24:25]
	v_add_co_u32_e32 v244, vcc, s97, v10
	s_nop 1
	v_addc_co_u32_e32 v245, vcc, 0, v11, vcc
	global_load_ushort v228, v[244:245], off offset:512
	v_add_co_u32_e32 v244, vcc, s79, v10
	s_nop 1
	v_addc_co_u32_e32 v245, vcc, 0, v11, vcc
	global_load_ushort v229, v[244:245], off offset:1280
	v_add_co_u32_e32 v244, vcc, 0x9000, v10
	s_nop 1
	v_addc_co_u32_e32 v245, vcc, 0, v11, vcc
	global_load_ushort v230, v[244:245], off offset:2048
	v_add_co_u32_e32 v244, vcc, 0xc000, v10
	s_nop 1
	v_addc_co_u32_e32 v245, vcc, 0, v11, vcc
	global_load_ushort v231, v[244:245], off offset:2816
	v_add_co_u32_e32 v244, vcc, 0xf000, v10
	s_nop 1
	v_addc_co_u32_e32 v245, vcc, 0, v11, vcc
	global_load_ushort v232, v[244:245], off offset:3584
	v_add_co_u32_e32 v244, vcc, 0x13000, v10
	s_nop 1
	v_addc_co_u32_e32 v245, vcc, 0, v11, vcc
	global_load_ushort v233, v[244:245], off offset:256
	v_add_co_u32_e32 v244, vcc, 0x16000, v10
	s_nop 1
	v_addc_co_u32_e32 v245, vcc, 0, v11, vcc
	global_load_ushort v234, v[244:245], off offset:1024
	v_add_co_u32_e32 v244, vcc, 0x19000, v10
	s_nop 1
	v_addc_co_u32_e32 v245, vcc, 0, v11, vcc
	global_load_ushort v235, v[244:245], off offset:1792
	v_add_co_u32_e32 v244, vcc, 0x1c000, v10
	s_nop 1
	v_addc_co_u32_e32 v245, vcc, 0, v11, vcc
	global_load_ushort v236, v[244:245], off offset:2560
	v_add_co_u32_e32 v244, vcc, 0x1f000, v10
	s_nop 1
	v_addc_co_u32_e32 v245, vcc, 0, v11, vcc
	global_load_ushort v237, v[244:245], off offset:3328
	v_add_co_u32_e32 v244, vcc, 0x23000, v10
	s_nop 1
	v_addc_co_u32_e32 v245, vcc, 0, v11, vcc
	global_load_ushort v238, v[244:245], off
	v_add_co_u32_e32 v244, vcc, 0x26000, v10
	s_nop 1
	v_addc_co_u32_e32 v245, vcc, 0, v11, vcc
	global_load_ushort v239, v[244:245], off offset:768
	v_add_co_u32_e32 v244, vcc, 0x29000, v10
	s_nop 1
	v_addc_co_u32_e32 v245, vcc, 0, v11, vcc
	global_load_ushort v240, v[244:245], off offset:1536
	v_add_co_u32_e32 v244, vcc, 0x2c000, v10
	s_nop 1
	v_addc_co_u32_e32 v245, vcc, 0, v11, vcc
	global_load_ushort v241, v[244:245], off offset:2304
	v_add_co_u32_e32 v244, vcc, 0x2f000, v10
	s_nop 1
	v_addc_co_u32_e32 v245, vcc, 0, v11, vcc
	global_load_ushort v242, v[244:245], off offset:3072
	v_add_co_u32_e32 v244, vcc, 0x32000, v10
	s_nop 1
	v_addc_co_u32_e32 v245, vcc, 0, v11, vcc
	global_load_ushort v243, v[244:245], off offset:3840
	s_mov_b32 s8, 0xbfb8aa3b
	s_nop 0
	s_mov_b32 s14, 0x3f317217
	s_mov_b32 s9, 0x7f800000
	v_mov_b32_e32 v24, 0x41b17218
	s_mov_b32 s13, s25
	s_mov_b32 s11, 0
	v_readlane_b32 s37, v251, 3
	v_readlane_b32 s38, v251, 4
	v_readlane_b32 s39, v251, 5
	v_readlane_b32 s40, v251, 6
	v_readlane_b32 s41, v251, 7
	v_readlane_b32 s44, v251, 10
	v_readlane_b32 s45, v251, 11
	v_readlane_b32 s46, v251, 12
	v_readlane_b32 s47, v251, 13
	v_readlane_b32 s48, v251, 14
	v_readlane_b32 s49, v251, 15
	v_readlane_b32 s50, v251, 16
	v_readlane_b32 s51, v251, 17
	v_readlane_b32 s81, v253, 13
	v_readlane_b32 s82, v253, 14
	v_readlane_b32 s83, v253, 15
	v_readlane_b32 s84, v253, 16
	v_readlane_b32 s85, v253, 17
	v_readlane_b32 s88, v253, 20
	v_readlane_b32 s89, v253, 21
	v_readlane_b32 s90, v253, 22
	v_readlane_b32 s91, v253, 23
	v_readlane_b32 s92, v253, 24
	v_readlane_b32 s93, v253, 25
	v_readlane_b32 s94, v253, 26
	v_readlane_b32 s95, v253, 27
	s_waitcnt vmcnt(15)
	v_cvt_f32_f16_e32 v4, v228
	v_add_f32_e32 v4, v0, v4
	v_min_f32_e32 v5, 0, v4
	v_mul_f32_e64 v4, |v4|, s8
	v_exp_f32_e32 v4, v4
	s_nop 0
	v_add_f32_e32 v4, 1.0, v4
	v_cmp_gt_f32_e32 vcc, s56, v4
	s_nop 1
	v_cndmask_b32_e64 v6, 0, 32, vcc
	v_ldexp_f32 v4, v4, v6
	v_log_f32_e32 v4, v4
	s_nop 0
	v_mul_f32_e32 v6, 0x3f317217, v4
	v_fma_f32 v6, v4, s14, -v6
	v_fmac_f32_e32 v6, 0x3377d1cf, v4
	v_fmac_f32_e32 v6, 0x3f317217, v4
	v_cmp_lt_f32_e64 s[0:1], |v4|, s9
	s_nop 1
	v_cndmask_b32_e64 v4, v4, v6, s[0:1]
	v_cndmask_b32_e32 v6, 0, v24, vcc
	v_sub_f32_e32 v4, v4, v6
	v_sub_f32_e32 v6, v5, v4
	s_nop 1
	s_waitcnt vmcnt(14)
	v_cvt_f32_f16_e32 v4, v229
	v_add_f32_e32 v4, v0, v4
	v_min_f32_e32 v5, 0, v4
	v_mul_f32_e64 v4, |v4|, s8
	v_exp_f32_e32 v4, v4
	s_nop 0
	v_add_f32_e32 v4, 1.0, v4
	v_cmp_gt_f32_e32 vcc, s56, v4
	s_nop 1
	v_cndmask_b32_e64 v7, 0, 32, vcc
	v_ldexp_f32 v4, v4, v7
	v_log_f32_e32 v4, v4
	s_nop 0
	v_mul_f32_e32 v7, 0x3f317217, v4
	v_fma_f32 v7, v4, s14, -v7
	v_fmac_f32_e32 v7, 0x3377d1cf, v4
	v_fmac_f32_e32 v7, 0x3f317217, v4
	v_cmp_lt_f32_e64 s[0:1], |v4|, s9
	s_nop 1
	v_cndmask_b32_e64 v4, v4, v7, s[0:1]
	v_cndmask_b32_e32 v7, 0, v24, vcc
	v_sub_f32_e32 v4, v4, v7
	v_sub_f32_e32 v5, v5, v4
	v_add_f32_e32 v4, 0, v6
	v_add_f32_e32 v5, v4, v5
	s_nop 0
	s_waitcnt vmcnt(13)
; DI float bf2f(u16 v) { return (float)__builtin_bit_cast(_Float16, v); }
; DI void cumsum_item(const Params& p, int l, int item, char* lds) {
;     ...
;   float v[16], run = 0.f;
; #pragma unroll
;   for (int i = 0; i < 16; ++i) {
;     const float f = bf2f(zf[(size_t)i * ZS]) + bfv;
;     const float ls = fminf(f, 0.f) - __logf(1.f + __expf(-fabsf(f)));
;     run += ls;
;     v[i] = run;
	v_cvt_f32_f16_e32 v6, v230
	v_add_f32_e32 v6, v0, v6
	v_min_f32_e32 v7, 0, v6
	v_mul_f32_e64 v6, |v6|, s8
	v_exp_f32_e32 v6, v6
	s_nop 0
	v_add_f32_e32 v6, 1.0, v6
	v_cmp_gt_f32_e32 vcc, s56, v6
	s_nop 1
	v_cndmask_b32_e64 v8, 0, 32, vcc
	v_ldexp_f32 v6, v6, v8
	v_log_f32_e32 v6, v6
	s_nop 0
	v_mul_f32_e32 v8, 0x3f317217, v6
	v_fma_f32 v8, v6, s14, -v8
	v_fmac_f32_e32 v8, 0x3377d1cf, v6
	v_fmac_f32_e32 v8, 0x3f317217, v6
	v_cmp_lt_f32_e64 s[0:1], |v6|, s9
	s_nop 1
	v_cndmask_b32_e64 v6, v6, v8, s[0:1]
	v_cndmask_b32_e32 v8, 0, v24, vcc
	v_sub_f32_e32 v6, v6, v8
	v_sub_f32_e32 v8, v7, v6
	s_nop 1
	s_waitcnt vmcnt(12)
	v_cvt_f32_f16_e32 v6, v231
	v_add_f32_e32 v6, v0, v6
	v_min_f32_e32 v7, 0, v6
	v_mul_f32_e64 v6, |v6|, s8
	v_exp_f32_e32 v6, v6
	s_nop 0
	v_add_f32_e32 v6, 1.0, v6
	v_cmp_gt_f32_e32 vcc, s56, v6
	s_nop 1
	v_cndmask_b32_e64 v9, 0, 32, vcc
	v_ldexp_f32 v6, v6, v9
	v_log_f32_e32 v6, v6
	s_nop 0
	v_mul_f32_e32 v9, 0x3f317217, v6
	v_fma_f32 v9, v6, s14, -v9
	v_fmac_f32_e32 v9, 0x3377d1cf, v6
	v_fmac_f32_e32 v9, 0x3f317217, v6
	v_cmp_lt_f32_e64 s[0:1], |v6|, s9
	s_nop 1
	v_cndmask_b32_e64 v6, v6, v9, s[0:1]
	v_cndmask_b32_e32 v9, 0, v24, vcc
	v_sub_f32_e32 v6, v6, v9
	v_sub_f32_e32 v7, v7, v6
	v_add_f32_e32 v6, v5, v8
	v_add_f32_e32 v7, v6, v7
	s_nop 0
	s_waitcnt vmcnt(11)
	v_cvt_f32_f16_e32 v8, v232
	v_add_f32_e32 v8, v0, v8
	v_min_f32_e32 v9, 0, v8
	v_mul_f32_e64 v8, |v8|, s8
	v_exp_f32_e32 v8, v8
	s_nop 0
	v_add_f32_e32 v8, 1.0, v8
	v_cmp_gt_f32_e32 vcc, s56, v8
	s_nop 1
	v_cndmask_b32_e64 v12, 0, 32, vcc
	v_ldexp_f32 v8, v8, v12
	v_log_f32_e32 v8, v8
	s_nop 0
	v_mul_f32_e32 v12, 0x3f317217, v8
	v_fma_f32 v12, v8, s14, -v12
	v_fmac_f32_e32 v12, 0x3377d1cf, v8
	v_fmac_f32_e32 v12, 0x3f317217, v8
	v_cmp_lt_f32_e64 s[0:1], |v8|, s9
	s_nop 1
	v_cndmask_b32_e64 v8, v8, v12, s[0:1]
	v_cndmask_b32_e32 v12, 0, v24, vcc
	v_sub_f32_e32 v8, v8, v12
	v_sub_f32_e32 v12, v9, v8
	s_nop 1
	s_waitcnt vmcnt(10)
	v_cvt_f32_f16_e32 v8, v233
	v_add_f32_e32 v8, v0, v8
	v_min_f32_e32 v9, 0, v8
	v_mul_f32_e64 v8, |v8|, s8
	v_exp_f32_e32 v8, v8
	s_nop 0
	v_add_f32_e32 v8, 1.0, v8
	v_cmp_gt_f32_e32 vcc, s56, v8
	s_nop 1
	v_cndmask_b32_e64 v13, 0, 32, vcc
	v_ldexp_f32 v8, v8, v13
	v_log_f32_e32 v8, v8
	s_nop 0
	v_mul_f32_e32 v13, 0x3f317217, v8
	v_fma_f32 v13, v8, s14, -v13
	v_fmac_f32_e32 v13, 0x3377d1cf, v8
	v_fmac_f32_e32 v13, 0x3f317217, v8
	v_cmp_lt_f32_e64 s[0:1], |v8|, s9
	s_nop 1
	v_cndmask_b32_e64 v8, v8, v13, s[0:1]
	v_cndmask_b32_e32 v13, 0, v24, vcc
	v_sub_f32_e32 v8, v8, v13
	v_sub_f32_e32 v9, v9, v8
	v_add_f32_e32 v8, v7, v12
	v_add_f32_e32 v9, v8, v9
	s_nop 0
	s_waitcnt vmcnt(9)
	v_cvt_f32_f16_e32 v12, v234
	v_add_f32_e32 v12, v0, v12
	v_min_f32_e32 v13, 0, v12
	v_mul_f32_e64 v12, |v12|, s8
	v_exp_f32_e32 v12, v12
	s_nop 0
	v_add_f32_e32 v12, 1.0, v12
	v_cmp_gt_f32_e32 vcc, s56, v12
	s_nop 1
	v_cndmask_b32_e64 v14, 0, 32, vcc
	v_ldexp_f32 v12, v12, v14
	v_log_f32_e32 v12, v12
	s_nop 0
	v_mul_f32_e32 v14, 0x3f317217, v12
	v_fma_f32 v14, v12, s14, -v14
	v_fmac_f32_e32 v14, 0x3377d1cf, v12
	v_fmac_f32_e32 v14, 0x3f317217, v12
	v_cmp_lt_f32_e64 s[0:1], |v12|, s9
	s_nop 1
	v_cndmask_b32_e64 v12, v12, v14, s[0:1]
	v_cndmask_b32_e32 v14, 0, v24, vcc
	v_sub_f32_e32 v12, v12, v14
	v_sub_f32_e32 v14, v13, v12
	s_nop 1
	s_waitcnt vmcnt(8)
	v_cvt_f32_f16_e32 v12, v235
	v_add_f32_e32 v12, v0, v12
	v_min_f32_e32 v13, 0, v12
	v_mul_f32_e64 v12, |v12|, s8
	v_exp_f32_e32 v12, v12
	s_nop 0
	v_add_f32_e32 v12, 1.0, v12
	v_cmp_gt_f32_e32 vcc, s56, v12
	s_nop 1
	v_cndmask_b32_e64 v15, 0, 32, vcc
	v_ldexp_f32 v12, v12, v15
	v_log_f32_e32 v12, v12
	s_nop 0
	v_mul_f32_e32 v15, 0x3f317217, v12
	v_fma_f32 v15, v12, s14, -v15
	v_fmac_f32_e32 v15, 0x3377d1cf, v12
	v_fmac_f32_e32 v15, 0x3f317217, v12
	v_cmp_lt_f32_e64 s[0:1], |v12|, s9
	s_nop 1
	v_cndmask_b32_e64 v12, v12, v15, s[0:1]
	v_cndmask_b32_e32 v15, 0, v24, vcc
	v_sub_f32_e32 v12, v12, v15
	v_sub_f32_e32 v13, v13, v12
	v_add_f32_e32 v12, v9, v14
	v_add_f32_e32 v13, v12, v13
	s_nop 0
	s_waitcnt vmcnt(7)
	v_cvt_f32_f16_e32 v14, v236
	v_add_f32_e32 v14, v0, v14
	v_min_f32_e32 v15, 0, v14
	v_mul_f32_e64 v14, |v14|, s8
	v_exp_f32_e32 v14, v14
	s_nop 0
	v_add_f32_e32 v14, 1.0, v14
	v_cmp_gt_f32_e32 vcc, s56, v14
	s_nop 1
	v_cndmask_b32_e64 v16, 0, 32, vcc
	v_ldexp_f32 v14, v14, v16
	v_log_f32_e32 v14, v14
	s_nop 0
	v_mul_f32_e32 v16, 0x3f317217, v14
	v_fma_f32 v16, v14, s14, -v16
	v_fmac_f32_e32 v16, 0x3377d1cf, v14
	v_fmac_f32_e32 v16, 0x3f317217, v14
	v_cmp_lt_f32_e64 s[0:1], |v14|, s9
	s_nop 1
	v_cndmask_b32_e64 v14, v14, v16, s[0:1]
	v_cndmask_b32_e32 v16, 0, v24, vcc
	v_sub_f32_e32 v14, v14, v16
	v_sub_f32_e32 v16, v15, v14
	s_nop 1
	s_waitcnt vmcnt(6)
; DI float bf2f(u16 v) { return (float)__builtin_bit_cast(_Float16, v); }
; DI void cumsum_item(const Params& p, int l, int item, char* lds) {
;     ...
;   float v[16], run = 0.f;
; #pragma unroll
;   for (int i = 0; i < 16; ++i) {
;     const float f = bf2f(zf[(size_t)i * ZS]) + bfv;
;     const float ls = fminf(f, 0.f) - __logf(1.f + __expf(-fabsf(f)));
;     run += ls;
;     v[i] = run;
;   }
;   part[tid] = run;
;   __syncthreads();
;   float pre = 0.f;
;   for (int i = 0; i < tid; ++i) pre += part[i];
	v_cvt_f32_f16_e32 v14, v237
	v_add_f32_e32 v14, v0, v14
	v_min_f32_e32 v15, 0, v14
	v_mul_f32_e64 v14, |v14|, s8
	v_exp_f32_e32 v14, v14
	s_nop 0
	v_add_f32_e32 v14, 1.0, v14
	v_cmp_gt_f32_e32 vcc, s56, v14
	s_nop 1
	v_cndmask_b32_e64 v17, 0, 32, vcc
	v_ldexp_f32 v14, v14, v17
	v_log_f32_e32 v14, v14
	s_nop 0
	v_mul_f32_e32 v17, 0x3f317217, v14
	v_fma_f32 v17, v14, s14, -v17
	v_fmac_f32_e32 v17, 0x3377d1cf, v14
	v_fmac_f32_e32 v17, 0x3f317217, v14
	v_cmp_lt_f32_e64 s[0:1], |v14|, s9
	s_nop 1
	v_cndmask_b32_e64 v14, v14, v17, s[0:1]
	v_cndmask_b32_e32 v17, 0, v24, vcc
	v_sub_f32_e32 v14, v14, v17
	v_sub_f32_e32 v15, v15, v14
	v_add_f32_e32 v14, v13, v16
	v_add_f32_e32 v15, v14, v15
	s_nop 0
	s_waitcnt vmcnt(5)
	v_cvt_f32_f16_e32 v16, v238
	v_add_f32_e32 v16, v0, v16
	v_min_f32_e32 v17, 0, v16
	v_mul_f32_e64 v16, |v16|, s8
	v_exp_f32_e32 v16, v16
	s_nop 0
	v_add_f32_e32 v16, 1.0, v16
	v_cmp_gt_f32_e32 vcc, s56, v16
	s_nop 1
	v_cndmask_b32_e64 v18, 0, 32, vcc
	v_ldexp_f32 v16, v16, v18
	v_log_f32_e32 v16, v16
	s_nop 0
	v_mul_f32_e32 v18, 0x3f317217, v16
	v_fma_f32 v18, v16, s14, -v18
	v_fmac_f32_e32 v18, 0x3377d1cf, v16
	v_fmac_f32_e32 v18, 0x3f317217, v16
	v_cmp_lt_f32_e64 s[0:1], |v16|, s9
	s_nop 1
	v_cndmask_b32_e64 v16, v16, v18, s[0:1]
	v_cndmask_b32_e32 v18, 0, v24, vcc
	v_sub_f32_e32 v16, v16, v18
	v_sub_f32_e32 v18, v17, v16
	s_nop 1
	s_waitcnt vmcnt(4)
	v_cvt_f32_f16_e32 v16, v239
	v_add_f32_e32 v16, v0, v16
	v_min_f32_e32 v17, 0, v16
	v_mul_f32_e64 v16, |v16|, s8
	v_exp_f32_e32 v16, v16
	s_nop 0
	v_add_f32_e32 v16, 1.0, v16
	v_cmp_gt_f32_e32 vcc, s56, v16
	s_nop 1
	v_cndmask_b32_e64 v19, 0, 32, vcc
	v_ldexp_f32 v16, v16, v19
	v_log_f32_e32 v16, v16
	s_nop 0
	v_mul_f32_e32 v19, 0x3f317217, v16
	v_fma_f32 v19, v16, s14, -v19
	v_fmac_f32_e32 v19, 0x3377d1cf, v16
	v_fmac_f32_e32 v19, 0x3f317217, v16
	v_cmp_lt_f32_e64 s[0:1], |v16|, s9
	s_nop 1
	v_cndmask_b32_e64 v16, v16, v19, s[0:1]
	v_cndmask_b32_e32 v19, 0, v24, vcc
	v_sub_f32_e32 v16, v16, v19
	v_sub_f32_e32 v17, v17, v16
	v_add_f32_e32 v16, v15, v18
	v_add_f32_e32 v17, v16, v17
	s_nop 0
	s_waitcnt vmcnt(3)
	v_cvt_f32_f16_e32 v18, v240
	v_add_f32_e32 v18, v0, v18
	v_min_f32_e32 v19, 0, v18
	v_mul_f32_e64 v18, |v18|, s8
	v_exp_f32_e32 v18, v18
	s_nop 0
	v_add_f32_e32 v18, 1.0, v18
	v_cmp_gt_f32_e32 vcc, s56, v18
	s_nop 1
	v_cndmask_b32_e64 v21, 0, 32, vcc
	v_ldexp_f32 v18, v18, v21
	v_log_f32_e32 v18, v18
	s_nop 0
	v_mul_f32_e32 v21, 0x3f317217, v18
	v_fma_f32 v21, v18, s14, -v21
	v_fmac_f32_e32 v21, 0x3377d1cf, v18
	v_fmac_f32_e32 v21, 0x3f317217, v18
	v_cmp_lt_f32_e64 s[0:1], |v18|, s9
	s_nop 1
	v_cndmask_b32_e64 v18, v18, v21, s[0:1]
	v_cndmask_b32_e32 v21, 0, v24, vcc
	v_sub_f32_e32 v18, v18, v21
	v_sub_f32_e32 v21, v19, v18
	s_nop 1
	s_waitcnt vmcnt(2)
	v_cvt_f32_f16_e32 v18, v241
	v_add_f32_e32 v18, v0, v18
	v_min_f32_e32 v19, 0, v18
	v_mul_f32_e64 v18, |v18|, s8
	v_exp_f32_e32 v18, v18
	s_nop 0
	v_add_f32_e32 v18, 1.0, v18
	v_cmp_gt_f32_e32 vcc, s56, v18
	s_nop 1
	v_cndmask_b32_e64 v22, 0, 32, vcc
	v_ldexp_f32 v18, v18, v22
	v_log_f32_e32 v18, v18
	s_nop 0
	v_mul_f32_e32 v22, 0x3f317217, v18
	v_fma_f32 v22, v18, s14, -v22
	v_fmac_f32_e32 v22, 0x3377d1cf, v18
	v_fmac_f32_e32 v22, 0x3f317217, v18
	v_cmp_lt_f32_e64 s[0:1], |v18|, s9
	s_nop 1
	v_cndmask_b32_e64 v18, v18, v22, s[0:1]
	v_cndmask_b32_e32 v22, 0, v24, vcc
	v_sub_f32_e32 v18, v18, v22
	v_sub_f32_e32 v19, v19, v18
	s_nop 0
	v_add_f32_e32 v18, v17, v21
	v_add_f32_e32 v19, v18, v19
	s_waitcnt vmcnt(1)
	v_cvt_f32_f16_e32 v21, v242
	v_add_f32_e32 v21, v0, v21
	v_min_f32_e32 v22, 0, v21
	v_mul_f32_e64 v21, |v21|, s8
	v_exp_f32_e32 v21, v21
	s_nop 0
	v_add_f32_e32 v21, 1.0, v21
	v_cmp_gt_f32_e32 vcc, s56, v21
	s_nop 1
	v_cndmask_b32_e64 v23, 0, 32, vcc
	v_ldexp_f32 v21, v21, v23
	v_log_f32_e32 v21, v21
	s_nop 0
	v_mul_f32_e32 v23, 0x3f317217, v21
	v_fma_f32 v23, v21, s14, -v23
	v_fmac_f32_e32 v23, 0x3377d1cf, v21
	v_fmac_f32_e32 v23, 0x3f317217, v21
	v_cmp_lt_f32_e64 s[0:1], |v21|, s9
	s_nop 1
	v_cndmask_b32_e64 v21, v21, v23, s[0:1]
	v_cndmask_b32_e32 v23, 0, v24, vcc
	v_sub_f32_e32 v21, v21, v23
	s_nop 0
	v_sub_f32_e32 v21, v22, v21
	s_waitcnt vmcnt(0)
	v_cvt_f32_f16_e32 v10, v243
	v_add_f32_e32 v0, v0, v10
	v_min_f32_e32 v10, 0, v0
	v_mul_f32_e64 v0, |v0|, s8
	v_exp_f32_e32 v0, v0
	s_nop 0
	v_add_f32_e32 v0, 1.0, v0
	v_cmp_gt_f32_e32 vcc, s56, v0
	s_nop 1
	v_cndmask_b32_e64 v11, 0, 32, vcc
	v_ldexp_f32 v0, v0, v11
	v_log_f32_e32 v0, v0
	s_nop 0
	v_mul_f32_e32 v11, 0x3f317217, v0
	v_fma_f32 v11, v0, s14, -v11
	v_fmac_f32_e32 v11, 0x3377d1cf, v0
	v_fmac_f32_e32 v11, 0x3f317217, v0
	v_cmp_lt_f32_e64 s[0:1], |v0|, s9
	s_nop 1
	v_cndmask_b32_e64 v0, v0, v11, s[0:1]
	v_cndmask_b32_e32 v11, 0, v24, vcc
	v_sub_f32_e32 v0, v0, v11
	v_sub_f32_e32 v0, v10, v0
	v_add_f32_e32 v10, v19, v21
	v_add_f32_e32 v11, v10, v0
	v_lshlrev_b32_e32 v0, 2, v20
	ds_write_b32 v0, v11
	v_cmp_lt_i32_e32 vcc, 0, v20
	v_mov_b32_e32 v0, 0
	s_waitcnt lgkmcnt(0)
	s_barrier
	s_and_saveexec_b64 s[0:1], vcc
	s_cbranch_execz .LBB0_338
	s_mov_b64 s[8:9], 0
	v_mov_b32_e32 v0, 0

; DI void compress_item(const Params& p, int l, int item, char* lds) {
;     ...
;   {
;     if (tid < 128) {
;       float a = 0.f;
; #pragma unroll 8
;       for (int kc = 0; kc < 32; ++kc) a += POSP(l)[(size_t)(kv * 32 + kc) * 128 + tid];
;       posw[tid] = a;
;     }
;     __syncthreads();
.LBB0_414:
	s_andn2_b64 vcc, exec, s[0:1]
	s_cbranch_vccnz .LBB0_288
	v_mov_b32_e32 v162, v209
	s_movk_i32 s0, 0x80
	s_nop 0
	v_cmp_gt_i32_e32 vcc, s0, v162
	s_and_saveexec_b64 s[0:1], vcc
	s_cbranch_execz .LBB0_419
	s_and_b32 s8, s12, 1
	s_lshl_b32 s8, s8, 14
	s_add_u32 s8, s18, s8
	v_ashrrev_i32_e32 v163, 31, v162
	s_addc_u32 s9, s19, 0
	v_lshl_add_u64 v[2:3], v[162:163], 2, s[8:9]
	v_mov_b32_e32 v0, 0
	s_mov_b64 s[8:9], 0
	s_movk_i32 s8, 0x1000
	v_lshl_add_u64 v[4:5], v[2:3], 0, s[8:9]
	s_movk_i32 s8, 0x2000
	v_lshl_add_u64 v[244:245], v[2:3], 0, s[8:9]
	s_movk_i32 s8, 0x3000
	v_lshl_add_u64 v[246:247], v[2:3], 0, s[8:9]
	global_load_dword v228, v[2:3], off
	global_load_dword v229, v[2:3], off offset:512
	global_load_dword v230, v[2:3], off offset:1024
	global_load_dword v231, v[2:3], off offset:1536
	global_load_dword v232, v[2:3], off offset:2048
	global_load_dword v233, v[2:3], off offset:2560
	global_load_dword v234, v[2:3], off offset:3072
	global_load_dword v235, v[2:3], off offset:3584
	global_load_dword v236, v[4:5], off
	global_load_dword v237, v[4:5], off offset:512
	global_load_dword v238, v[4:5], off offset:1024
	global_load_dword v239, v[4:5], off offset:1536
	global_load_dword v240, v[4:5], off offset:2048
	global_load_dword v241, v[4:5], off offset:2560
	global_load_dword v242, v[4:5], off offset:3072
	global_load_dword v243, v[4:5], off offset:3584
	s_waitcnt vmcnt(15)
	v_add_f32_e32 v0, v0, v228
	global_load_dword v228, v[244:245], off
	s_waitcnt vmcnt(15)
	v_add_f32_e32 v0, v0, v229
	global_load_dword v229, v[244:245], off offset:512
	s_waitcnt vmcnt(15)
	v_add_f32_e32 v0, v0, v230
	global_load_dword v230, v[244:245], off offset:1024
	s_waitcnt vmcnt(15)
	v_add_f32_e32 v0, v0, v231
	global_load_dword v231, v[244:245], off offset:1536
	s_waitcnt vmcnt(15)
	v_add_f32_e32 v0, v0, v232
	global_load_dword v232, v[244:245], off offset:2048
	s_waitcnt vmcnt(15)
	v_add_f32_e32 v0, v0, v233
	global_load_dword v233, v[244:245], off offset:2560
	s_waitcnt vmcnt(15)
	v_add_f32_e32 v0, v0, v234
	global_load_dword v234, v[244:245], off offset:3072
	s_waitcnt vmcnt(15)
	v_add_f32_e32 v0, v0, v235
	global_load_dword v235, v[244:245], off offset:3584
	s_waitcnt vmcnt(15)
	v_add_f32_e32 v0, v0, v236
	global_load_dword v236, v[246:247], off
	s_waitcnt vmcnt(15)
	v_add_f32_e32 v0, v0, v237
	global_load_dword v237, v[246:247], off offset:512
	s_waitcnt vmcnt(15)
	v_add_f32_e32 v0, v0, v238
	global_load_dword v238, v[246:247], off offset:1024
	s_waitcnt vmcnt(15)
	v_add_f32_e32 v0, v0, v239
	global_load_dword v239, v[246:247], off offset:1536
	s_waitcnt vmcnt(15)
	v_add_f32_e32 v0, v0, v240
	global_load_dword v240, v[246:247], off offset:2048
	s_waitcnt vmcnt(15)
	v_add_f32_e32 v0, v0, v241
	global_load_dword v241, v[246:247], off offset:2560
	s_waitcnt vmcnt(15)
	v_add_f32_e32 v0, v0, v242
	global_load_dword v242, v[246:247], off offset:3072
	s_waitcnt vmcnt(15)
	v_add_f32_e32 v0, v0, v243
	global_load_dword v243, v[246:247], off offset:3584
	s_waitcnt vmcnt(15)
	v_add_f32_e32 v0, v0, v228
	s_waitcnt vmcnt(14)
	v_add_f32_e32 v0, v0, v229
	s_waitcnt vmcnt(13)
	v_add_f32_e32 v0, v0, v230
	s_waitcnt vmcnt(12)
	v_add_f32_e32 v0, v0, v231
	s_waitcnt vmcnt(11)
	v_add_f32_e32 v0, v0, v232
	s_waitcnt vmcnt(10)
	v_add_f32_e32 v0, v0, v233
	s_waitcnt vmcnt(9)
	v_add_f32_e32 v0, v0, v234
	s_waitcnt vmcnt(8)
	v_add_f32_e32 v0, v0, v235
	s_waitcnt vmcnt(7)
	v_add_f32_e32 v0, v0, v236
	s_waitcnt vmcnt(6)
	v_add_f32_e32 v0, v0, v237
	s_waitcnt vmcnt(5)
	v_add_f32_e32 v0, v0, v238
	s_waitcnt vmcnt(4)
	v_add_f32_e32 v0, v0, v239
	s_waitcnt vmcnt(3)
	v_add_f32_e32 v0, v0, v240
	s_waitcnt vmcnt(2)
	v_add_f32_e32 v0, v0, v241
	s_waitcnt vmcnt(1)
	v_add_f32_e32 v0, v0, v242
	s_waitcnt vmcnt(0)
	v_add_f32_e32 v0, v0, v243
	v_lshlrev_b32_e32 v2, 2, v162
	ds_write_b32 v2, v0
